# v17 plus batched gate and partial-sum loads in the two branch-projection GEMM epilogues (was 32 serialized load-wait-store steps each)
# speedup vs baseline: 1.0194x; 1.0019x over previous
; __device__ __forceinline__ u32x2 pk4(f32x4 v) { u32x2 w; w.x = pk2(v[0], v[1]); w.y = pk2(v[2], v[3]); return w; }
; __device__ __forceinline__ f32x4 ldbf4(const bf16_t* p) { const u32x2 w = *(const u32x2*)p; f32x4 v; v[0] = __uint_as_float(w.x << 16); v[1] = __uint_as_float(w.x & 0xffff0000u); v[2] = __uint_as_float(w.y << 16); v[3] = __uint_as_float(w.y & 0xffff0000u); return v; }
;     __device__ __forceinline__ void operator()(const f32x4 (&acc)[2][2][4][2], const Unit& u, int wr, int wc, int fr, int fq) const {
;         const int lr0 = wr * 64 + fr, c0 = u.pn * 256 + wc * 32 + 4 * fq;
; #pragma unroll
;         for (int ai = 0; ai < 2; ++ai)
; #pragma unroll
;             for (int m = 0; m < 4; ++m) { const size_t ro = (size_t)(u.pm * 256 + ai * 128 + m * 16 + lr0) * 1024 + c0;
; #pragma unroll
;                 for (int bj = 0; bj < 2; ++bj)
; #pragma unroll
;                     for (int n = 0; n < 2; ++n) { const f32x4 g = ldbf4(GA + ro + bj * 128 + n * 16); *(u32x2*)(T1 + ro + bj * 128 + n * 16) = pk4(acc[ai][bj][m][n] * g); } }
;     }
.LBB0_847:
	v_lshl_add_u32 v138, s65, 8, v140
	v_lshl_or_b32 v136, s66, 8, v142
	v_lshlrev_b32_e32 v150, 1, v136
	v_lshl_add_u32 v160, v138, 11, v150
	v_add_u32_e32 v161, 0x8000, v160
	v_add_u32_e32 v162, 0x10000, v160
	v_add_u32_e32 v163, 0x18000, v160
	v_add_u32_e32 v164, 0x40000, v160
	v_add_u32_e32 v165, 0x48000, v160
	v_add_u32_e32 v166, 0x50000, v160
	v_add_u32_e32 v167, 0x58000, v160
	s_and_b64 vcc, exec, s[38:39]
	s_mov_b64 s[16:17], -1
	global_load_dwordx2 v[198:199], v160, s[18:19]
	global_load_dwordx2 v[200:201], v160, s[18:19] offset:32
	global_load_dwordx2 v[202:203], v160, s[18:19] offset:256
	global_load_dwordx2 v[204:205], v160, s[18:19] offset:288
	global_load_dwordx2 v[206:207], v161, s[18:19]
	global_load_dwordx2 v[208:209], v161, s[18:19] offset:32
	global_load_dwordx2 v[210:211], v161, s[18:19] offset:256
	global_load_dwordx2 v[212:213], v161, s[18:19] offset:288
	global_load_dwordx2 v[214:215], v162, s[18:19]
	global_load_dwordx2 v[216:217], v162, s[18:19] offset:32
	global_load_dwordx2 v[218:219], v162, s[18:19] offset:256
	global_load_dwordx2 v[220:221], v162, s[18:19] offset:288
	global_load_dwordx2 v[222:223], v163, s[18:19]
	global_load_dwordx2 v[224:225], v163, s[18:19] offset:32
	global_load_dwordx2 v[226:227], v163, s[18:19] offset:256
	global_load_dwordx2 v[228:229], v163, s[18:19] offset:288
	global_load_dwordx2 v[230:231], v164, s[18:19]
	global_load_dwordx2 v[232:233], v164, s[18:19] offset:32
	global_load_dwordx2 v[234:235], v164, s[18:19] offset:256
	global_load_dwordx2 v[236:237], v164, s[18:19] offset:288
	global_load_dwordx2 v[238:239], v165, s[18:19]
	global_load_dwordx2 v[240:241], v165, s[18:19] offset:32
	global_load_dwordx2 v[242:243], v165, s[18:19] offset:256
	global_load_dwordx2 v[244:245], v165, s[18:19] offset:288
	global_load_dwordx2 v[246:247], v166, s[18:19]
	global_load_dwordx2 v[248:249], v166, s[18:19] offset:32
	global_load_dwordx2 v[250:251], v166, s[18:19] offset:256
	global_load_dwordx2 v[252:253], v166, s[18:19] offset:288
	global_load_dwordx2 v[182:183], v167, s[18:19]
	global_load_dwordx2 v[184:185], v167, s[18:19] offset:32
	global_load_dwordx2 v[186:187], v167, s[18:19] offset:256
	global_load_dwordx2 v[190:191], v167, s[18:19] offset:288
	s_waitcnt vmcnt(0)
	v_lshlrev_b32_e32 v168, 16, v198
	v_and_b32_e32 v169, 0xffff0000, v198
	v_lshlrev_b32_e32 v170, 16, v199
	v_and_b32_e32 v171, 0xffff0000, v199
	v_pk_mul_f32 v[126:127], v[126:127], v[170:171]
	v_pk_mul_f32 v[124:125], v[124:125], v[168:169]
	s_nop 0
	v_cvt_pk_bf16_f32 v124, v124, v125
	v_cvt_pk_bf16_f32 v125, v126, v127
	global_store_dwordx2 v160, v[124:125], s[28:29]
	v_lshlrev_b32_e32 v172, 16, v200
	v_and_b32_e32 v173, 0xffff0000, v200
	v_lshlrev_b32_e32 v174, 16, v201
	v_and_b32_e32 v175, 0xffff0000, v201
	v_pk_mul_f32 v[122:123], v[122:123], v[174:175]
	v_pk_mul_f32 v[120:121], v[120:121], v[172:173]
	s_nop 0
	v_cvt_pk_bf16_f32 v120, v120, v121
	v_cvt_pk_bf16_f32 v121, v122, v123
	global_store_dwordx2 v160, v[120:121], s[28:29] offset:32
	v_lshlrev_b32_e32 v168, 16, v202
	v_and_b32_e32 v169, 0xffff0000, v202
	v_lshlrev_b32_e32 v170, 16, v203
	v_and_b32_e32 v171, 0xffff0000, v203
	v_pk_mul_f32 v[118:119], v[118:119], v[170:171]
	v_pk_mul_f32 v[116:117], v[116:117], v[168:169]
	s_nop 0
	v_cvt_pk_bf16_f32 v116, v116, v117
	v_cvt_pk_bf16_f32 v117, v118, v119
	global_store_dwordx2 v160, v[116:117], s[28:29] offset:256
	v_lshlrev_b32_e32 v172, 16, v204
	v_and_b32_e32 v173, 0xffff0000, v204
	v_lshlrev_b32_e32 v174, 16, v205
	v_and_b32_e32 v175, 0xffff0000, v205
	v_pk_mul_f32 v[114:115], v[114:115], v[174:175]
	v_pk_mul_f32 v[112:113], v[112:113], v[172:173]
	s_nop 0
	v_cvt_pk_bf16_f32 v112, v112, v113
	v_cvt_pk_bf16_f32 v113, v114, v115
	global_store_dwordx2 v160, v[112:113], s[28:29] offset:288
	v_lshlrev_b32_e32 v168, 16, v206
	v_and_b32_e32 v169, 0xffff0000, v206
	v_lshlrev_b32_e32 v170, 16, v207
	v_and_b32_e32 v171, 0xffff0000, v207
	v_pk_mul_f32 v[110:111], v[110:111], v[170:171]
	v_pk_mul_f32 v[108:109], v[108:109], v[168:169]
	s_nop 0
	v_cvt_pk_bf16_f32 v108, v108, v109
	v_cvt_pk_bf16_f32 v109, v110, v111
	global_store_dwordx2 v161, v[108:109], s[28:29]
	v_lshlrev_b32_e32 v172, 16, v208
	v_and_b32_e32 v173, 0xffff0000, v208
	v_lshlrev_b32_e32 v174, 16, v209
	v_and_b32_e32 v175, 0xffff0000, v209
	v_pk_mul_f32 v[106:107], v[106:107], v[174:175]
	v_pk_mul_f32 v[104:105], v[104:105], v[172:173]
	s_nop 0
	v_cvt_pk_bf16_f32 v104, v104, v105
	v_cvt_pk_bf16_f32 v105, v106, v107
	global_store_dwordx2 v161, v[104:105], s[28:29] offset:32
	v_lshlrev_b32_e32 v168, 16, v210
	v_and_b32_e32 v169, 0xffff0000, v210
	v_lshlrev_b32_e32 v170, 16, v211
	v_and_b32_e32 v171, 0xffff0000, v211
	v_pk_mul_f32 v[102:103], v[102:103], v[170:171]
	v_pk_mul_f32 v[100:101], v[100:101], v[168:169]
	s_nop 0
	v_cvt_pk_bf16_f32 v100, v100, v101
	v_cvt_pk_bf16_f32 v101, v102, v103
	global_store_dwordx2 v161, v[100:101], s[28:29] offset:256
	v_lshlrev_b32_e32 v172, 16, v212
	v_and_b32_e32 v173, 0xffff0000, v212
	v_lshlrev_b32_e32 v174, 16, v213
	v_and_b32_e32 v175, 0xffff0000, v213
	v_pk_mul_f32 v[98:99], v[98:99], v[174:175]
	v_pk_mul_f32 v[96:97], v[96:97], v[172:173]
	s_nop 0
	v_cvt_pk_bf16_f32 v96, v96, v97
	v_cvt_pk_bf16_f32 v97, v98, v99
	global_store_dwordx2 v161, v[96:97], s[28:29] offset:288
	v_lshlrev_b32_e32 v168, 16, v214
	v_and_b32_e32 v169, 0xffff0000, v214
	v_lshlrev_b32_e32 v170, 16, v215
	v_and_b32_e32 v171, 0xffff0000, v215
	v_pk_mul_f32 v[94:95], v[94:95], v[170:171]
	v_pk_mul_f32 v[92:93], v[92:93], v[168:169]
	s_nop 0
	v_cvt_pk_bf16_f32 v92, v92, v93
	v_cvt_pk_bf16_f32 v93, v94, v95
	global_store_dwordx2 v162, v[92:93], s[28:29]
; __device__ __forceinline__ u32x2 pk4(f32x4 v) { u32x2 w; w.x = pk2(v[0], v[1]); w.y = pk2(v[2], v[3]); return w; }
; __device__ __forceinline__ f32x4 ldbf4(const bf16_t* p) { const u32x2 w = *(const u32x2*)p; f32x4 v; v[0] = __uint_as_float(w.x << 16); v[1] = __uint_as_float(w.x & 0xffff0000u); v[2] = __uint_as_float(w.y << 16); v[3] = __uint_as_float(w.y & 0xffff0000u); return v; }
;     __device__ __forceinline__ void operator()(const f32x4 (&acc)[2][2][4][2], const Unit& u, int wr, int wc, int fr, int fq) const {
;         const int lr0 = wr * 64 + fr, c0 = u.pn * 256 + wc * 32 + 4 * fq;
; #pragma unroll
;         for (int ai = 0; ai < 2; ++ai)
; #pragma unroll
;             for (int m = 0; m < 4; ++m) { const size_t ro = (size_t)(u.pm * 256 + ai * 128 + m * 16 + lr0) * 1024 + c0;
; #pragma unroll
;                 for (int bj = 0; bj < 2; ++bj)
; #pragma unroll
;                     for (int n = 0; n < 2; ++n) { const f32x4 g = ldbf4(GA + ro + bj * 128 + n * 16); *(u32x2*)(T1 + ro + bj * 128 + n * 16) = pk4(acc[ai][bj][m][n] * g); } }
;     }
	v_lshlrev_b32_e32 v172, 16, v216
	v_and_b32_e32 v173, 0xffff0000, v216
	v_lshlrev_b32_e32 v174, 16, v217
	v_and_b32_e32 v175, 0xffff0000, v217
	v_pk_mul_f32 v[90:91], v[90:91], v[174:175]
	v_pk_mul_f32 v[88:89], v[88:89], v[172:173]
	s_nop 0
	v_cvt_pk_bf16_f32 v88, v88, v89
	v_cvt_pk_bf16_f32 v89, v90, v91
	global_store_dwordx2 v162, v[88:89], s[28:29] offset:32
	v_lshlrev_b32_e32 v168, 16, v218
	v_and_b32_e32 v169, 0xffff0000, v218
	v_lshlrev_b32_e32 v170, 16, v219
	v_and_b32_e32 v171, 0xffff0000, v219
	v_pk_mul_f32 v[86:87], v[86:87], v[170:171]
	v_pk_mul_f32 v[84:85], v[84:85], v[168:169]
	s_nop 0
	v_cvt_pk_bf16_f32 v84, v84, v85
	v_cvt_pk_bf16_f32 v85, v86, v87
	global_store_dwordx2 v162, v[84:85], s[28:29] offset:256
	v_lshlrev_b32_e32 v172, 16, v220
	v_and_b32_e32 v173, 0xffff0000, v220
	v_lshlrev_b32_e32 v174, 16, v221
	v_and_b32_e32 v175, 0xffff0000, v221
	v_pk_mul_f32 v[82:83], v[82:83], v[174:175]
	v_pk_mul_f32 v[80:81], v[80:81], v[172:173]
	s_nop 0
	v_cvt_pk_bf16_f32 v80, v80, v81
	v_cvt_pk_bf16_f32 v81, v82, v83
	global_store_dwordx2 v162, v[80:81], s[28:29] offset:288
	v_lshlrev_b32_e32 v168, 16, v222
	v_and_b32_e32 v169, 0xffff0000, v222
	v_lshlrev_b32_e32 v170, 16, v223
	v_and_b32_e32 v171, 0xffff0000, v223
	v_pk_mul_f32 v[78:79], v[78:79], v[170:171]
	v_pk_mul_f32 v[76:77], v[76:77], v[168:169]
	s_nop 0
	v_cvt_pk_bf16_f32 v76, v76, v77
	v_cvt_pk_bf16_f32 v77, v78, v79
	global_store_dwordx2 v163, v[76:77], s[28:29]
	v_lshlrev_b32_e32 v172, 16, v224
	v_and_b32_e32 v173, 0xffff0000, v224
	v_lshlrev_b32_e32 v174, 16, v225
	v_and_b32_e32 v175, 0xffff0000, v225
	v_pk_mul_f32 v[74:75], v[74:75], v[174:175]
	v_pk_mul_f32 v[72:73], v[72:73], v[172:173]
	s_nop 0
	v_cvt_pk_bf16_f32 v72, v72, v73
	v_cvt_pk_bf16_f32 v73, v74, v75
	global_store_dwordx2 v163, v[72:73], s[28:29] offset:32
	v_lshlrev_b32_e32 v168, 16, v226
	v_and_b32_e32 v169, 0xffff0000, v226
	v_lshlrev_b32_e32 v170, 16, v227
	v_and_b32_e32 v171, 0xffff0000, v227
	v_pk_mul_f32 v[70:71], v[70:71], v[170:171]
	v_pk_mul_f32 v[68:69], v[68:69], v[168:169]
	s_nop 0
	v_cvt_pk_bf16_f32 v68, v68, v69
	v_cvt_pk_bf16_f32 v69, v70, v71
	global_store_dwordx2 v163, v[68:69], s[28:29] offset:256
	v_lshlrev_b32_e32 v172, 16, v228
	v_and_b32_e32 v173, 0xffff0000, v228
	v_lshlrev_b32_e32 v174, 16, v229
	v_and_b32_e32 v175, 0xffff0000, v229
	v_pk_mul_f32 v[66:67], v[66:67], v[174:175]
	v_pk_mul_f32 v[64:65], v[64:65], v[172:173]
	s_nop 0
	v_cvt_pk_bf16_f32 v64, v64, v65
	v_cvt_pk_bf16_f32 v65, v66, v67
	global_store_dwordx2 v163, v[64:65], s[28:29] offset:288
	v_lshlrev_b32_e32 v168, 16, v230
	v_and_b32_e32 v169, 0xffff0000, v230
	v_lshlrev_b32_e32 v170, 16, v231
	v_and_b32_e32 v171, 0xffff0000, v231
	v_pk_mul_f32 v[62:63], v[62:63], v[170:171]
	v_pk_mul_f32 v[60:61], v[60:61], v[168:169]
	s_nop 0
	v_cvt_pk_bf16_f32 v60, v60, v61
	v_cvt_pk_bf16_f32 v61, v62, v63
	global_store_dwordx2 v164, v[60:61], s[28:29]
	v_lshlrev_b32_e32 v172, 16, v232
	v_and_b32_e32 v173, 0xffff0000, v232
	v_lshlrev_b32_e32 v174, 16, v233
	v_and_b32_e32 v175, 0xffff0000, v233
	v_pk_mul_f32 v[58:59], v[58:59], v[174:175]
	v_pk_mul_f32 v[56:57], v[56:57], v[172:173]
	s_nop 0
	v_cvt_pk_bf16_f32 v56, v56, v57
	v_cvt_pk_bf16_f32 v57, v58, v59
	global_store_dwordx2 v164, v[56:57], s[28:29] offset:32
	v_lshlrev_b32_e32 v168, 16, v234
	v_and_b32_e32 v169, 0xffff0000, v234
	v_lshlrev_b32_e32 v170, 16, v235
	v_and_b32_e32 v171, 0xffff0000, v235
	v_pk_mul_f32 v[54:55], v[54:55], v[170:171]
	v_pk_mul_f32 v[52:53], v[52:53], v[168:169]
	s_nop 0
	v_cvt_pk_bf16_f32 v52, v52, v53
	v_cvt_pk_bf16_f32 v53, v54, v55
	global_store_dwordx2 v164, v[52:53], s[28:29] offset:256
	v_lshlrev_b32_e32 v172, 16, v236
	v_and_b32_e32 v173, 0xffff0000, v236
	v_lshlrev_b32_e32 v174, 16, v237
	v_and_b32_e32 v175, 0xffff0000, v237
	v_pk_mul_f32 v[50:51], v[50:51], v[174:175]
	v_pk_mul_f32 v[48:49], v[48:49], v[172:173]
	s_nop 0
	v_cvt_pk_bf16_f32 v48, v48, v49
	v_cvt_pk_bf16_f32 v49, v50, v51
	global_store_dwordx2 v164, v[48:49], s[28:29] offset:288
	v_lshlrev_b32_e32 v168, 16, v238
	v_and_b32_e32 v169, 0xffff0000, v238
	v_lshlrev_b32_e32 v170, 16, v239
	v_and_b32_e32 v171, 0xffff0000, v239
	v_pk_mul_f32 v[46:47], v[46:47], v[170:171]
	v_pk_mul_f32 v[44:45], v[44:45], v[168:169]
; __device__ __forceinline__ u32x2 pk4(f32x4 v) { u32x2 w; w.x = pk2(v[0], v[1]); w.y = pk2(v[2], v[3]); return w; }
; __device__ __forceinline__ f32x4 ldbf4(const bf16_t* p) { const u32x2 w = *(const u32x2*)p; f32x4 v; v[0] = __uint_as_float(w.x << 16); v[1] = __uint_as_float(w.x & 0xffff0000u); v[2] = __uint_as_float(w.y << 16); v[3] = __uint_as_float(w.y & 0xffff0000u); return v; }
;     __device__ __forceinline__ void operator()(const f32x4 (&acc)[2][2][4][2], const Unit& u, int wr, int wc, int fr, int fq) const {
;         const int lr0 = wr * 64 + fr, c0 = u.pn * 256 + wc * 32 + 4 * fq;
; #pragma unroll
;         for (int ai = 0; ai < 2; ++ai)
; #pragma unroll
;             for (int m = 0; m < 4; ++m) { const size_t ro = (size_t)(u.pm * 256 + ai * 128 + m * 16 + lr0) * 1024 + c0;
; #pragma unroll
;                 for (int bj = 0; bj < 2; ++bj)
; #pragma unroll
;                     for (int n = 0; n < 2; ++n) { const f32x4 g = ldbf4(GA + ro + bj * 128 + n * 16); *(u32x2*)(T1 + ro + bj * 128 + n * 16) = pk4(acc[ai][bj][m][n] * g); } }
;     }
	s_nop 0
	v_cvt_pk_bf16_f32 v44, v44, v45
	v_cvt_pk_bf16_f32 v45, v46, v47
	global_store_dwordx2 v165, v[44:45], s[28:29]
	v_lshlrev_b32_e32 v172, 16, v240
	v_and_b32_e32 v173, 0xffff0000, v240
	v_lshlrev_b32_e32 v174, 16, v241
	v_and_b32_e32 v175, 0xffff0000, v241
	v_pk_mul_f32 v[42:43], v[42:43], v[174:175]
	v_pk_mul_f32 v[40:41], v[40:41], v[172:173]
	s_nop 0
	v_cvt_pk_bf16_f32 v40, v40, v41
	v_cvt_pk_bf16_f32 v41, v42, v43
	global_store_dwordx2 v165, v[40:41], s[28:29] offset:32
	v_lshlrev_b32_e32 v168, 16, v242
	v_and_b32_e32 v169, 0xffff0000, v242
	v_lshlrev_b32_e32 v170, 16, v243
	v_and_b32_e32 v171, 0xffff0000, v243
	v_pk_mul_f32 v[38:39], v[38:39], v[170:171]
	v_pk_mul_f32 v[36:37], v[36:37], v[168:169]
	s_nop 0
	v_cvt_pk_bf16_f32 v36, v36, v37
	v_cvt_pk_bf16_f32 v37, v38, v39
	global_store_dwordx2 v165, v[36:37], s[28:29] offset:256
	v_lshlrev_b32_e32 v172, 16, v244
	v_and_b32_e32 v173, 0xffff0000, v244
	v_lshlrev_b32_e32 v174, 16, v245
	v_and_b32_e32 v175, 0xffff0000, v245
	v_pk_mul_f32 v[34:35], v[34:35], v[174:175]
	v_pk_mul_f32 v[32:33], v[32:33], v[172:173]
	s_nop 0
	v_cvt_pk_bf16_f32 v32, v32, v33
	v_cvt_pk_bf16_f32 v33, v34, v35
	global_store_dwordx2 v165, v[32:33], s[28:29] offset:288
	v_lshlrev_b32_e32 v168, 16, v246
	v_and_b32_e32 v169, 0xffff0000, v246
	v_lshlrev_b32_e32 v170, 16, v247
	v_and_b32_e32 v171, 0xffff0000, v247
	v_pk_mul_f32 v[30:31], v[30:31], v[170:171]
	v_pk_mul_f32 v[28:29], v[28:29], v[168:169]
	s_nop 0
	v_cvt_pk_bf16_f32 v28, v28, v29
	v_cvt_pk_bf16_f32 v29, v30, v31
	global_store_dwordx2 v166, v[28:29], s[28:29]
	v_lshlrev_b32_e32 v172, 16, v248
	v_and_b32_e32 v173, 0xffff0000, v248
	v_lshlrev_b32_e32 v174, 16, v249
	v_and_b32_e32 v175, 0xffff0000, v249
	v_pk_mul_f32 v[26:27], v[26:27], v[174:175]
	v_pk_mul_f32 v[24:25], v[24:25], v[172:173]
	s_nop 0
	v_cvt_pk_bf16_f32 v24, v24, v25
	v_cvt_pk_bf16_f32 v25, v26, v27
	global_store_dwordx2 v166, v[24:25], s[28:29] offset:32
	v_lshlrev_b32_e32 v168, 16, v250
	v_and_b32_e32 v169, 0xffff0000, v250
	v_lshlrev_b32_e32 v170, 16, v251
	v_and_b32_e32 v171, 0xffff0000, v251
	v_pk_mul_f32 v[22:23], v[22:23], v[170:171]
	v_pk_mul_f32 v[20:21], v[20:21], v[168:169]
	s_nop 0
	v_cvt_pk_bf16_f32 v20, v20, v21
	v_cvt_pk_bf16_f32 v21, v22, v23
	global_store_dwordx2 v166, v[20:21], s[28:29] offset:256
	v_lshlrev_b32_e32 v172, 16, v252
	v_and_b32_e32 v173, 0xffff0000, v252
	v_lshlrev_b32_e32 v174, 16, v253
	v_and_b32_e32 v175, 0xffff0000, v253
	v_pk_mul_f32 v[18:19], v[18:19], v[174:175]
	v_pk_mul_f32 v[16:17], v[16:17], v[172:173]
	s_nop 0
	v_cvt_pk_bf16_f32 v16, v16, v17
	v_cvt_pk_bf16_f32 v17, v18, v19
	global_store_dwordx2 v166, v[16:17], s[28:29] offset:288
	v_lshlrev_b32_e32 v168, 16, v182
	v_and_b32_e32 v169, 0xffff0000, v182
	v_lshlrev_b32_e32 v170, 16, v183
	v_and_b32_e32 v171, 0xffff0000, v183
	v_pk_mul_f32 v[14:15], v[14:15], v[170:171]
	v_pk_mul_f32 v[12:13], v[12:13], v[168:169]
	s_nop 0
	v_cvt_pk_bf16_f32 v12, v12, v13
	v_cvt_pk_bf16_f32 v13, v14, v15
	global_store_dwordx2 v167, v[12:13], s[28:29]
	v_lshlrev_b32_e32 v172, 16, v184
	v_and_b32_e32 v173, 0xffff0000, v184
	v_lshlrev_b32_e32 v174, 16, v185
	v_and_b32_e32 v175, 0xffff0000, v185
	v_pk_mul_f32 v[10:11], v[10:11], v[174:175]
	v_pk_mul_f32 v[8:9], v[8:9], v[172:173]
	s_nop 0
	v_cvt_pk_bf16_f32 v8, v8, v9
	v_cvt_pk_bf16_f32 v9, v10, v11
	global_store_dwordx2 v167, v[8:9], s[28:29] offset:32
	v_lshlrev_b32_e32 v168, 16, v186
	v_and_b32_e32 v169, 0xffff0000, v186
	v_lshlrev_b32_e32 v170, 16, v187
	v_and_b32_e32 v171, 0xffff0000, v187
	v_pk_mul_f32 v[6:7], v[6:7], v[170:171]
	v_pk_mul_f32 v[4:5], v[4:5], v[168:169]
	s_nop 0
	v_cvt_pk_bf16_f32 v4, v4, v5
	v_cvt_pk_bf16_f32 v5, v6, v7
	global_store_dwordx2 v167, v[4:5], s[28:29] offset:256
	v_lshlrev_b32_e32 v172, 16, v190
	v_and_b32_e32 v173, 0xffff0000, v190
	v_lshlrev_b32_e32 v174, 16, v191
	v_and_b32_e32 v175, 0xffff0000, v191
	v_pk_mul_f32 v[2:3], v[2:3], v[174:175]
	v_pk_mul_f32 v[0:1], v[0:1], v[172:173]
	s_nop 0
	v_cvt_pk_bf16_f32 v0, v0, v1
	v_cvt_pk_bf16_f32 v1, v2, v3
	global_store_dwordx2 v167, v[0:1], s[28:29] offset:288
	s_cbranch_vccnz .LBB0_831
	s_andn2_b64 vcc, exec, s[26:27]
	s_cbranch_vccnz .LBB0_830
	s_barrier
	s_branch .LBB0_830

; __device__ __forceinline__ u32x2 pk4(f32x4 v) { u32x2 w; w.x = pk2(v[0], v[1]); w.y = pk2(v[2], v[3]); return w; }
; __device__ __forceinline__ f32x4 ldbf4(const bf16_t* p) { const u32x2 w = *(const u32x2*)p; f32x4 v; v[0] = __uint_as_float(w.x << 16); v[1] = __uint_as_float(w.x & 0xffff0000u); v[2] = __uint_as_float(w.y << 16); v[3] = __uint_as_float(w.y & 0xffff0000u); return v; }
;     __device__ __forceinline__ void operator()(const f32x4 (&acc)[2][2][4][2], const Unit& u, int wr, int wc, int fr, int fq) const {
;         const int lr0 = wr * 64 + fr, c0 = u.pn * 256 + wc * 32 + 4 * fq;
; #pragma unroll
;         for (int ai = 0; ai < 2; ++ai)
; #pragma unroll
;             for (int m = 0; m < 4; ++m) { const size_t ro = (size_t)(u.pm * 256 + ai * 128 + m * 16 + lr0) * 1024 + c0;
; #pragma unroll
;                 for (int bj = 0; bj < 2; ++bj)
; #pragma unroll
;                     for (int n = 0; n < 2; ++n) { const f32x4 g = ldbf4(GB + ro + bj * 128 + n * 16), t = ldbf4(T1 + ro + bj * 128 + n * 16); *(u32x2*)(MM + ro + bj * 128 + n * 16) = pk4(t + acc[ai][bj][m][n] * g); } }
;     }
.LBB0_880:
	v_lshl_add_u32 v138, s67, 8, v140
	v_lshl_or_b32 v136, s71, 8, v142
	v_lshlrev_b32_e32 v150, 1, v136
	v_lshl_add_u32 v160, v138, 11, v150
	v_add_u32_e32 v161, 0x8000, v160
	v_add_u32_e32 v162, 0x10000, v160
	v_add_u32_e32 v163, 0x18000, v160
	v_add_u32_e32 v164, 0x40000, v160
	v_add_u32_e32 v165, 0x48000, v160
	v_add_u32_e32 v166, 0x50000, v160
	v_add_u32_e32 v167, 0x58000, v160
	s_and_b64 vcc, exec, s[38:39]
	s_mov_b64 s[16:17], -1
	global_load_dwordx2 v[198:199], v160, s[48:49]
	global_load_dwordx2 v[200:201], v160, s[48:49] offset:32
	global_load_dwordx2 v[202:203], v160, s[48:49] offset:256
	global_load_dwordx2 v[204:205], v160, s[48:49] offset:288
	global_load_dwordx2 v[206:207], v161, s[48:49]
	global_load_dwordx2 v[208:209], v161, s[48:49] offset:32
	global_load_dwordx2 v[210:211], v161, s[48:49] offset:256
	global_load_dwordx2 v[212:213], v161, s[48:49] offset:288
	global_load_dwordx2 v[214:215], v162, s[48:49]
	global_load_dwordx2 v[216:217], v162, s[48:49] offset:32
	global_load_dwordx2 v[218:219], v162, s[48:49] offset:256
	global_load_dwordx2 v[220:221], v162, s[48:49] offset:288
	global_load_dwordx2 v[222:223], v163, s[48:49]
	global_load_dwordx2 v[224:225], v163, s[48:49] offset:32
	global_load_dwordx2 v[226:227], v163, s[48:49] offset:256
	global_load_dwordx2 v[228:229], v163, s[48:49] offset:288
	global_load_dwordx2 v[230:231], v160, s[50:51]
	global_load_dwordx2 v[232:233], v160, s[50:51] offset:32
	global_load_dwordx2 v[234:235], v160, s[50:51] offset:256
	global_load_dwordx2 v[236:237], v160, s[50:51] offset:288
	global_load_dwordx2 v[238:239], v161, s[50:51]
	global_load_dwordx2 v[240:241], v161, s[50:51] offset:32
	global_load_dwordx2 v[242:243], v161, s[50:51] offset:256
	global_load_dwordx2 v[244:245], v161, s[50:51] offset:288
	global_load_dwordx2 v[246:247], v162, s[50:51]
	global_load_dwordx2 v[248:249], v162, s[50:51] offset:32
	global_load_dwordx2 v[250:251], v162, s[50:51] offset:256
	global_load_dwordx2 v[252:253], v162, s[50:51] offset:288
	global_load_dwordx2 v[182:183], v163, s[50:51]
	global_load_dwordx2 v[184:185], v163, s[50:51] offset:32
	global_load_dwordx2 v[186:187], v163, s[50:51] offset:256
	global_load_dwordx2 v[190:191], v163, s[50:51] offset:288
	s_waitcnt vmcnt(0)
	v_lshlrev_b32_e32 v168, 16, v198
	v_and_b32_e32 v169, 0xffff0000, v198
	v_lshlrev_b32_e32 v170, 16, v199
	v_and_b32_e32 v171, 0xffff0000, v199
	v_lshlrev_b32_e32 v172, 16, v230
	v_and_b32_e32 v173, 0xffff0000, v230
	v_lshlrev_b32_e32 v174, 16, v231
	v_and_b32_e32 v175, 0xffff0000, v231
	v_pk_fma_f32 v[126:127], v[126:127], v[170:171], v[174:175]
	v_pk_fma_f32 v[124:125], v[124:125], v[168:169], v[172:173]
	s_nop 0
	v_cvt_pk_bf16_f32 v124, v124, v125
	v_cvt_pk_bf16_f32 v125, v126, v127
	global_store_dwordx2 v160, v[124:125], s[52:53]
	v_lshlrev_b32_e32 v168, 16, v200
	v_and_b32_e32 v169, 0xffff0000, v200
	v_lshlrev_b32_e32 v170, 16, v201
	v_and_b32_e32 v171, 0xffff0000, v201
	v_lshlrev_b32_e32 v172, 16, v232
	v_and_b32_e32 v173, 0xffff0000, v232
	v_lshlrev_b32_e32 v174, 16, v233
	v_and_b32_e32 v175, 0xffff0000, v233
	v_pk_fma_f32 v[122:123], v[122:123], v[170:171], v[174:175]
	v_pk_fma_f32 v[120:121], v[120:121], v[168:169], v[172:173]
	s_nop 0
	v_cvt_pk_bf16_f32 v120, v120, v121
	v_cvt_pk_bf16_f32 v121, v122, v123
	global_store_dwordx2 v160, v[120:121], s[52:53] offset:32
	v_lshlrev_b32_e32 v168, 16, v202
	v_and_b32_e32 v169, 0xffff0000, v202
	v_lshlrev_b32_e32 v170, 16, v203
	v_and_b32_e32 v171, 0xffff0000, v203
	v_lshlrev_b32_e32 v172, 16, v234
	v_and_b32_e32 v173, 0xffff0000, v234
	v_lshlrev_b32_e32 v174, 16, v235
	v_and_b32_e32 v175, 0xffff0000, v235
	v_pk_fma_f32 v[118:119], v[118:119], v[170:171], v[174:175]
	v_pk_fma_f32 v[116:117], v[116:117], v[168:169], v[172:173]
	s_nop 0
	v_cvt_pk_bf16_f32 v116, v116, v117
	v_cvt_pk_bf16_f32 v117, v118, v119
	global_store_dwordx2 v160, v[116:117], s[52:53] offset:256
	v_lshlrev_b32_e32 v168, 16, v204
	v_and_b32_e32 v169, 0xffff0000, v204
	v_lshlrev_b32_e32 v170, 16, v205
	v_and_b32_e32 v171, 0xffff0000, v205
	v_lshlrev_b32_e32 v172, 16, v236
	v_and_b32_e32 v173, 0xffff0000, v236
	v_lshlrev_b32_e32 v174, 16, v237
	v_and_b32_e32 v175, 0xffff0000, v237
	v_pk_fma_f32 v[114:115], v[114:115], v[170:171], v[174:175]
	v_pk_fma_f32 v[112:113], v[112:113], v[168:169], v[172:173]
	s_nop 0
	v_cvt_pk_bf16_f32 v112, v112, v113
	v_cvt_pk_bf16_f32 v113, v114, v115
	global_store_dwordx2 v160, v[112:113], s[52:53] offset:288
	v_lshlrev_b32_e32 v168, 16, v206
	v_and_b32_e32 v169, 0xffff0000, v206
	v_lshlrev_b32_e32 v170, 16, v207
	v_and_b32_e32 v171, 0xffff0000, v207
	v_lshlrev_b32_e32 v172, 16, v238
	v_and_b32_e32 v173, 0xffff0000, v238
	v_lshlrev_b32_e32 v174, 16, v239
	v_and_b32_e32 v175, 0xffff0000, v239
	v_pk_fma_f32 v[110:111], v[110:111], v[170:171], v[174:175]
	v_pk_fma_f32 v[108:109], v[108:109], v[168:169], v[172:173]
	s_nop 0
	v_cvt_pk_bf16_f32 v108, v108, v109
	v_cvt_pk_bf16_f32 v109, v110, v111
	global_store_dwordx2 v161, v[108:109], s[52:53]
	v_lshlrev_b32_e32 v168, 16, v208
	v_and_b32_e32 v169, 0xffff0000, v208
	v_lshlrev_b32_e32 v170, 16, v209
	v_and_b32_e32 v171, 0xffff0000, v209
	v_lshlrev_b32_e32 v172, 16, v240
	v_and_b32_e32 v173, 0xffff0000, v240
	v_lshlrev_b32_e32 v174, 16, v241
	v_and_b32_e32 v175, 0xffff0000, v241
	v_pk_fma_f32 v[106:107], v[106:107], v[170:171], v[174:175]
	v_pk_fma_f32 v[104:105], v[104:105], v[168:169], v[172:173]
	s_nop 0
	v_cvt_pk_bf16_f32 v104, v104, v105
	v_cvt_pk_bf16_f32 v105, v106, v107
	global_store_dwordx2 v161, v[104:105], s[52:53] offset:32
	v_lshlrev_b32_e32 v168, 16, v210
	v_and_b32_e32 v169, 0xffff0000, v210
	v_lshlrev_b32_e32 v170, 16, v211
; __device__ __forceinline__ u32x2 pk4(f32x4 v) { u32x2 w; w.x = pk2(v[0], v[1]); w.y = pk2(v[2], v[3]); return w; }
; __device__ __forceinline__ f32x4 ldbf4(const bf16_t* p) { const u32x2 w = *(const u32x2*)p; f32x4 v; v[0] = __uint_as_float(w.x << 16); v[1] = __uint_as_float(w.x & 0xffff0000u); v[2] = __uint_as_float(w.y << 16); v[3] = __uint_as_float(w.y & 0xffff0000u); return v; }
;     __device__ __forceinline__ void operator()(const f32x4 (&acc)[2][2][4][2], const Unit& u, int wr, int wc, int fr, int fq) const {
;         const int lr0 = wr * 64 + fr, c0 = u.pn * 256 + wc * 32 + 4 * fq;
; #pragma unroll
;         for (int ai = 0; ai < 2; ++ai)
; #pragma unroll
;             for (int m = 0; m < 4; ++m) { const size_t ro = (size_t)(u.pm * 256 + ai * 128 + m * 16 + lr0) * 1024 + c0;
; #pragma unroll
;                 for (int bj = 0; bj < 2; ++bj)
; #pragma unroll
;                     for (int n = 0; n < 2; ++n) { const f32x4 g = ldbf4(GB + ro + bj * 128 + n * 16), t = ldbf4(T1 + ro + bj * 128 + n * 16); *(u32x2*)(MM + ro + bj * 128 + n * 16) = pk4(t + acc[ai][bj][m][n] * g); } }
;     }
	v_and_b32_e32 v171, 0xffff0000, v211
	v_lshlrev_b32_e32 v172, 16, v242
	v_and_b32_e32 v173, 0xffff0000, v242
	v_lshlrev_b32_e32 v174, 16, v243
	v_and_b32_e32 v175, 0xffff0000, v243
	v_pk_fma_f32 v[102:103], v[102:103], v[170:171], v[174:175]
	v_pk_fma_f32 v[100:101], v[100:101], v[168:169], v[172:173]
	s_nop 0
	v_cvt_pk_bf16_f32 v100, v100, v101
	v_cvt_pk_bf16_f32 v101, v102, v103
	global_store_dwordx2 v161, v[100:101], s[52:53] offset:256
	v_lshlrev_b32_e32 v168, 16, v212
	v_and_b32_e32 v169, 0xffff0000, v212
	v_lshlrev_b32_e32 v170, 16, v213
	v_and_b32_e32 v171, 0xffff0000, v213
	v_lshlrev_b32_e32 v172, 16, v244
	v_and_b32_e32 v173, 0xffff0000, v244
	v_lshlrev_b32_e32 v174, 16, v245
	v_and_b32_e32 v175, 0xffff0000, v245
	v_pk_fma_f32 v[98:99], v[98:99], v[170:171], v[174:175]
	v_pk_fma_f32 v[96:97], v[96:97], v[168:169], v[172:173]
	s_nop 0
	v_cvt_pk_bf16_f32 v96, v96, v97
	v_cvt_pk_bf16_f32 v97, v98, v99
	global_store_dwordx2 v161, v[96:97], s[52:53] offset:288
	v_lshlrev_b32_e32 v168, 16, v214
	v_and_b32_e32 v169, 0xffff0000, v214
	v_lshlrev_b32_e32 v170, 16, v215
	v_and_b32_e32 v171, 0xffff0000, v215
	v_lshlrev_b32_e32 v172, 16, v246
	v_and_b32_e32 v173, 0xffff0000, v246
	v_lshlrev_b32_e32 v174, 16, v247
	v_and_b32_e32 v175, 0xffff0000, v247
	v_pk_fma_f32 v[94:95], v[94:95], v[170:171], v[174:175]
	v_pk_fma_f32 v[92:93], v[92:93], v[168:169], v[172:173]
	s_nop 0
	v_cvt_pk_bf16_f32 v92, v92, v93
	v_cvt_pk_bf16_f32 v93, v94, v95
	global_store_dwordx2 v162, v[92:93], s[52:53]
	v_lshlrev_b32_e32 v168, 16, v216
	v_and_b32_e32 v169, 0xffff0000, v216
	v_lshlrev_b32_e32 v170, 16, v217
	v_and_b32_e32 v171, 0xffff0000, v217
	v_lshlrev_b32_e32 v172, 16, v248
	v_and_b32_e32 v173, 0xffff0000, v248
	v_lshlrev_b32_e32 v174, 16, v249
	v_and_b32_e32 v175, 0xffff0000, v249
	v_pk_fma_f32 v[90:91], v[90:91], v[170:171], v[174:175]
	v_pk_fma_f32 v[88:89], v[88:89], v[168:169], v[172:173]
	s_nop 0
	v_cvt_pk_bf16_f32 v88, v88, v89
	v_cvt_pk_bf16_f32 v89, v90, v91
	global_store_dwordx2 v162, v[88:89], s[52:53] offset:32
	v_lshlrev_b32_e32 v168, 16, v218
	v_and_b32_e32 v169, 0xffff0000, v218
	v_lshlrev_b32_e32 v170, 16, v219
	v_and_b32_e32 v171, 0xffff0000, v219
	v_lshlrev_b32_e32 v172, 16, v250
	v_and_b32_e32 v173, 0xffff0000, v250
	v_lshlrev_b32_e32 v174, 16, v251
	v_and_b32_e32 v175, 0xffff0000, v251
	v_pk_fma_f32 v[86:87], v[86:87], v[170:171], v[174:175]
	v_pk_fma_f32 v[84:85], v[84:85], v[168:169], v[172:173]
	s_nop 0
	v_cvt_pk_bf16_f32 v84, v84, v85
	v_cvt_pk_bf16_f32 v85, v86, v87
	global_store_dwordx2 v162, v[84:85], s[52:53] offset:256
	v_lshlrev_b32_e32 v168, 16, v220
	v_and_b32_e32 v169, 0xffff0000, v220
	v_lshlrev_b32_e32 v170, 16, v221
	v_and_b32_e32 v171, 0xffff0000, v221
	v_lshlrev_b32_e32 v172, 16, v252
	v_and_b32_e32 v173, 0xffff0000, v252
	v_lshlrev_b32_e32 v174, 16, v253
	v_and_b32_e32 v175, 0xffff0000, v253
	v_pk_fma_f32 v[82:83], v[82:83], v[170:171], v[174:175]
	v_pk_fma_f32 v[80:81], v[80:81], v[168:169], v[172:173]
	s_nop 0
	v_cvt_pk_bf16_f32 v80, v80, v81
	v_cvt_pk_bf16_f32 v81, v82, v83
	global_store_dwordx2 v162, v[80:81], s[52:53] offset:288
	v_lshlrev_b32_e32 v168, 16, v222
	v_and_b32_e32 v169, 0xffff0000, v222
	v_lshlrev_b32_e32 v170, 16, v223
	v_and_b32_e32 v171, 0xffff0000, v223
	v_lshlrev_b32_e32 v172, 16, v182
	v_and_b32_e32 v173, 0xffff0000, v182
	v_lshlrev_b32_e32 v174, 16, v183
	v_and_b32_e32 v175, 0xffff0000, v183
	v_pk_fma_f32 v[78:79], v[78:79], v[170:171], v[174:175]
	v_pk_fma_f32 v[76:77], v[76:77], v[168:169], v[172:173]
	s_nop 0
	v_cvt_pk_bf16_f32 v76, v76, v77
	v_cvt_pk_bf16_f32 v77, v78, v79
	global_store_dwordx2 v163, v[76:77], s[52:53]
	v_lshlrev_b32_e32 v168, 16, v224
	v_and_b32_e32 v169, 0xffff0000, v224
	v_lshlrev_b32_e32 v170, 16, v225
	v_and_b32_e32 v171, 0xffff0000, v225
	v_lshlrev_b32_e32 v172, 16, v184
	v_and_b32_e32 v173, 0xffff0000, v184
	v_lshlrev_b32_e32 v174, 16, v185
	v_and_b32_e32 v175, 0xffff0000, v185
	v_pk_fma_f32 v[74:75], v[74:75], v[170:171], v[174:175]
	v_pk_fma_f32 v[72:73], v[72:73], v[168:169], v[172:173]
	s_nop 0
	v_cvt_pk_bf16_f32 v72, v72, v73
	v_cvt_pk_bf16_f32 v73, v74, v75
	global_store_dwordx2 v163, v[72:73], s[52:53] offset:32
	v_lshlrev_b32_e32 v168, 16, v226
	v_and_b32_e32 v169, 0xffff0000, v226
	v_lshlrev_b32_e32 v170, 16, v227
	v_and_b32_e32 v171, 0xffff0000, v227
	v_lshlrev_b32_e32 v172, 16, v186
	v_and_b32_e32 v173, 0xffff0000, v186
	v_lshlrev_b32_e32 v174, 16, v187
	v_and_b32_e32 v175, 0xffff0000, v187
	v_pk_fma_f32 v[70:71], v[70:71], v[170:171], v[174:175]
	v_pk_fma_f32 v[68:69], v[68:69], v[168:169], v[172:173]
	s_nop 0
	v_cvt_pk_bf16_f32 v68, v68, v69
	v_cvt_pk_bf16_f32 v69, v70, v71
	global_store_dwordx2 v163, v[68:69], s[52:53] offset:256
	v_lshlrev_b32_e32 v168, 16, v228
	v_and_b32_e32 v169, 0xffff0000, v228
	v_lshlrev_b32_e32 v170, 16, v229
	v_and_b32_e32 v171, 0xffff0000, v229
	v_lshlrev_b32_e32 v172, 16, v190
	v_and_b32_e32 v173, 0xffff0000, v190
	v_lshlrev_b32_e32 v174, 16, v191
	v_and_b32_e32 v175, 0xffff0000, v191
	v_pk_fma_f32 v[66:67], v[66:67], v[170:171], v[174:175]
	v_pk_fma_f32 v[64:65], v[64:65], v[168:169], v[172:173]
	s_nop 0
	v_cvt_pk_bf16_f32 v64, v64, v65
	v_cvt_pk_bf16_f32 v65, v66, v67
	global_store_dwordx2 v163, v[64:65], s[52:53] offset:288
	global_load_dwordx2 v[198:199], v164, s[48:49]
	global_load_dwordx2 v[200:201], v164, s[48:49] offset:32
	global_load_dwordx2 v[202:203], v164, s[48:49] offset:256
	global_load_dwordx2 v[204:205], v164, s[48:49] offset:288
	global_load_dwordx2 v[206:207], v165, s[48:49]
	global_load_dwordx2 v[208:209], v165, s[48:49] offset:32
	global_load_dwordx2 v[210:211], v165, s[48:49] offset:256
	global_load_dwordx2 v[212:213], v165, s[48:49] offset:288
	global_load_dwordx2 v[214:215], v166, s[48:49]
	global_load_dwordx2 v[216:217], v166, s[48:49] offset:32
	global_load_dwordx2 v[218:219], v166, s[48:49] offset:256
	global_load_dwordx2 v[220:221], v166, s[48:49] offset:288
	global_load_dwordx2 v[222:223], v167, s[48:49]
	global_load_dwordx2 v[224:225], v167, s[48:49] offset:32
	global_load_dwordx2 v[226:227], v167, s[48:49] offset:256
	global_load_dwordx2 v[228:229], v167, s[48:49] offset:288
	global_load_dwordx2 v[230:231], v164, s[50:51]
	global_load_dwordx2 v[232:233], v164, s[50:51] offset:32
	global_load_dwordx2 v[234:235], v164, s[50:51] offset:256
	global_load_dwordx2 v[236:237], v164, s[50:51] offset:288
	global_load_dwordx2 v[238:239], v165, s[50:51]
	global_load_dwordx2 v[240:241], v165, s[50:51] offset:32
	global_load_dwordx2 v[242:243], v165, s[50:51] offset:256
	global_load_dwordx2 v[244:245], v165, s[50:51] offset:288
	global_load_dwordx2 v[246:247], v166, s[50:51]
	global_load_dwordx2 v[248:249], v166, s[50:51] offset:32
	global_load_dwordx2 v[250:251], v166, s[50:51] offset:256
	global_load_dwordx2 v[252:253], v166, s[50:51] offset:288
	global_load_dwordx2 v[182:183], v167, s[50:51]
	global_load_dwordx2 v[184:185], v167, s[50:51] offset:32
	global_load_dwordx2 v[186:187], v167, s[50:51] offset:256
	global_load_dwordx2 v[190:191], v167, s[50:51] offset:288
	s_waitcnt vmcnt(0)
; __device__ __forceinline__ u32x2 pk4(f32x4 v) { u32x2 w; w.x = pk2(v[0], v[1]); w.y = pk2(v[2], v[3]); return w; }
; __device__ __forceinline__ f32x4 ldbf4(const bf16_t* p) { const u32x2 w = *(const u32x2*)p; f32x4 v; v[0] = __uint_as_float(w.x << 16); v[1] = __uint_as_float(w.x & 0xffff0000u); v[2] = __uint_as_float(w.y << 16); v[3] = __uint_as_float(w.y & 0xffff0000u); return v; }
;     __device__ __forceinline__ void operator()(const f32x4 (&acc)[2][2][4][2], const Unit& u, int wr, int wc, int fr, int fq) const {
;         const int lr0 = wr * 64 + fr, c0 = u.pn * 256 + wc * 32 + 4 * fq;
; #pragma unroll
;         for (int ai = 0; ai < 2; ++ai)
; #pragma unroll
;             for (int m = 0; m < 4; ++m) { const size_t ro = (size_t)(u.pm * 256 + ai * 128 + m * 16 + lr0) * 1024 + c0;
; #pragma unroll
;                 for (int bj = 0; bj < 2; ++bj)
; #pragma unroll
;                     for (int n = 0; n < 2; ++n) { const f32x4 g = ldbf4(GB + ro + bj * 128 + n * 16), t = ldbf4(T1 + ro + bj * 128 + n * 16); *(u32x2*)(MM + ro + bj * 128 + n * 16) = pk4(t + acc[ai][bj][m][n] * g); } }
;     }
	v_lshlrev_b32_e32 v168, 16, v198
	v_and_b32_e32 v169, 0xffff0000, v198
	v_lshlrev_b32_e32 v170, 16, v199
	v_and_b32_e32 v171, 0xffff0000, v199
	v_lshlrev_b32_e32 v172, 16, v230
	v_and_b32_e32 v173, 0xffff0000, v230
	v_lshlrev_b32_e32 v174, 16, v231
	v_and_b32_e32 v175, 0xffff0000, v231
	v_pk_fma_f32 v[62:63], v[62:63], v[170:171], v[174:175]
	v_pk_fma_f32 v[60:61], v[60:61], v[168:169], v[172:173]
	s_nop 0
	v_cvt_pk_bf16_f32 v60, v60, v61
	v_cvt_pk_bf16_f32 v61, v62, v63
	global_store_dwordx2 v164, v[60:61], s[52:53]
	v_lshlrev_b32_e32 v168, 16, v200
	v_and_b32_e32 v169, 0xffff0000, v200
	v_lshlrev_b32_e32 v170, 16, v201
	v_and_b32_e32 v171, 0xffff0000, v201
	v_lshlrev_b32_e32 v172, 16, v232
	v_and_b32_e32 v173, 0xffff0000, v232
	v_lshlrev_b32_e32 v174, 16, v233
	v_and_b32_e32 v175, 0xffff0000, v233
	v_pk_fma_f32 v[58:59], v[58:59], v[170:171], v[174:175]
	v_pk_fma_f32 v[56:57], v[56:57], v[168:169], v[172:173]
	s_nop 0
	v_cvt_pk_bf16_f32 v56, v56, v57
	v_cvt_pk_bf16_f32 v57, v58, v59
	global_store_dwordx2 v164, v[56:57], s[52:53] offset:32
	v_lshlrev_b32_e32 v168, 16, v202
	v_and_b32_e32 v169, 0xffff0000, v202
	v_lshlrev_b32_e32 v170, 16, v203
	v_and_b32_e32 v171, 0xffff0000, v203
	v_lshlrev_b32_e32 v172, 16, v234
	v_and_b32_e32 v173, 0xffff0000, v234
	v_lshlrev_b32_e32 v174, 16, v235
	v_and_b32_e32 v175, 0xffff0000, v235
	v_pk_fma_f32 v[54:55], v[54:55], v[170:171], v[174:175]
	v_pk_fma_f32 v[52:53], v[52:53], v[168:169], v[172:173]
	s_nop 0
	v_cvt_pk_bf16_f32 v52, v52, v53
	v_cvt_pk_bf16_f32 v53, v54, v55
	global_store_dwordx2 v164, v[52:53], s[52:53] offset:256
	v_lshlrev_b32_e32 v168, 16, v204
	v_and_b32_e32 v169, 0xffff0000, v204
	v_lshlrev_b32_e32 v170, 16, v205
	v_and_b32_e32 v171, 0xffff0000, v205
	v_lshlrev_b32_e32 v172, 16, v236
	v_and_b32_e32 v173, 0xffff0000, v236
	v_lshlrev_b32_e32 v174, 16, v237
	v_and_b32_e32 v175, 0xffff0000, v237
	v_pk_fma_f32 v[50:51], v[50:51], v[170:171], v[174:175]
	v_pk_fma_f32 v[48:49], v[48:49], v[168:169], v[172:173]
	s_nop 0
	v_cvt_pk_bf16_f32 v48, v48, v49
	v_cvt_pk_bf16_f32 v49, v50, v51
	global_store_dwordx2 v164, v[48:49], s[52:53] offset:288
	v_lshlrev_b32_e32 v168, 16, v206
	v_and_b32_e32 v169, 0xffff0000, v206
	v_lshlrev_b32_e32 v170, 16, v207
	v_and_b32_e32 v171, 0xffff0000, v207
	v_lshlrev_b32_e32 v172, 16, v238
	v_and_b32_e32 v173, 0xffff0000, v238
	v_lshlrev_b32_e32 v174, 16, v239
	v_and_b32_e32 v175, 0xffff0000, v239
	v_pk_fma_f32 v[46:47], v[46:47], v[170:171], v[174:175]
	v_pk_fma_f32 v[44:45], v[44:45], v[168:169], v[172:173]
	s_nop 0
	v_cvt_pk_bf16_f32 v44, v44, v45
	v_cvt_pk_bf16_f32 v45, v46, v47
	global_store_dwordx2 v165, v[44:45], s[52:53]
	v_lshlrev_b32_e32 v168, 16, v208
	v_and_b32_e32 v169, 0xffff0000, v208
	v_lshlrev_b32_e32 v170, 16, v209
	v_and_b32_e32 v171, 0xffff0000, v209
	v_lshlrev_b32_e32 v172, 16, v240
	v_and_b32_e32 v173, 0xffff0000, v240
	v_lshlrev_b32_e32 v174, 16, v241
	v_and_b32_e32 v175, 0xffff0000, v241
	v_pk_fma_f32 v[42:43], v[42:43], v[170:171], v[174:175]
	v_pk_fma_f32 v[40:41], v[40:41], v[168:169], v[172:173]
	s_nop 0
	v_cvt_pk_bf16_f32 v40, v40, v41
	v_cvt_pk_bf16_f32 v41, v42, v43
	global_store_dwordx2 v165, v[40:41], s[52:53] offset:32
	v_lshlrev_b32_e32 v168, 16, v210
	v_and_b32_e32 v169, 0xffff0000, v210
	v_lshlrev_b32_e32 v170, 16, v211
	v_and_b32_e32 v171, 0xffff0000, v211
	v_lshlrev_b32_e32 v172, 16, v242
	v_and_b32_e32 v173, 0xffff0000, v242
	v_lshlrev_b32_e32 v174, 16, v243
	v_and_b32_e32 v175, 0xffff0000, v243
	v_pk_fma_f32 v[38:39], v[38:39], v[170:171], v[174:175]
	v_pk_fma_f32 v[36:37], v[36:37], v[168:169], v[172:173]
	s_nop 0
	v_cvt_pk_bf16_f32 v36, v36, v37
	v_cvt_pk_bf16_f32 v37, v38, v39
	global_store_dwordx2 v165, v[36:37], s[52:53] offset:256
	v_lshlrev_b32_e32 v168, 16, v212
	v_and_b32_e32 v169, 0xffff0000, v212
	v_lshlrev_b32_e32 v170, 16, v213
	v_and_b32_e32 v171, 0xffff0000, v213
	v_lshlrev_b32_e32 v172, 16, v244
	v_and_b32_e32 v173, 0xffff0000, v244
	v_lshlrev_b32_e32 v174, 16, v245
	v_and_b32_e32 v175, 0xffff0000, v245
	v_pk_fma_f32 v[34:35], v[34:35], v[170:171], v[174:175]
	v_pk_fma_f32 v[32:33], v[32:33], v[168:169], v[172:173]
	s_nop 0
	v_cvt_pk_bf16_f32 v32, v32, v33
	v_cvt_pk_bf16_f32 v33, v34, v35
	global_store_dwordx2 v165, v[32:33], s[52:53] offset:288
	v_lshlrev_b32_e32 v168, 16, v214
; __device__ __forceinline__ u32x2 pk4(f32x4 v) { u32x2 w; w.x = pk2(v[0], v[1]); w.y = pk2(v[2], v[3]); return w; }
; __device__ __forceinline__ f32x4 ldbf4(const bf16_t* p) { const u32x2 w = *(const u32x2*)p; f32x4 v; v[0] = __uint_as_float(w.x << 16); v[1] = __uint_as_float(w.x & 0xffff0000u); v[2] = __uint_as_float(w.y << 16); v[3] = __uint_as_float(w.y & 0xffff0000u); return v; }
;     __device__ __forceinline__ void operator()(const f32x4 (&acc)[2][2][4][2], const Unit& u, int wr, int wc, int fr, int fq) const {
;         const int lr0 = wr * 64 + fr, c0 = u.pn * 256 + wc * 32 + 4 * fq;
; #pragma unroll
;         for (int ai = 0; ai < 2; ++ai)
; #pragma unroll
;             for (int m = 0; m < 4; ++m) { const size_t ro = (size_t)(u.pm * 256 + ai * 128 + m * 16 + lr0) * 1024 + c0;
; #pragma unroll
;                 for (int bj = 0; bj < 2; ++bj)
; #pragma unroll
;                     for (int n = 0; n < 2; ++n) { const f32x4 g = ldbf4(GB + ro + bj * 128 + n * 16), t = ldbf4(T1 + ro + bj * 128 + n * 16); *(u32x2*)(MM + ro + bj * 128 + n * 16) = pk4(t + acc[ai][bj][m][n] * g); } }
;     }
	v_and_b32_e32 v169, 0xffff0000, v214
	v_lshlrev_b32_e32 v170, 16, v215
	v_and_b32_e32 v171, 0xffff0000, v215
	v_lshlrev_b32_e32 v172, 16, v246
	v_and_b32_e32 v173, 0xffff0000, v246
	v_lshlrev_b32_e32 v174, 16, v247
	v_and_b32_e32 v175, 0xffff0000, v247
	v_pk_fma_f32 v[30:31], v[30:31], v[170:171], v[174:175]
	v_pk_fma_f32 v[28:29], v[28:29], v[168:169], v[172:173]
	s_nop 0
	v_cvt_pk_bf16_f32 v28, v28, v29
	v_cvt_pk_bf16_f32 v29, v30, v31
	global_store_dwordx2 v166, v[28:29], s[52:53]
	v_lshlrev_b32_e32 v168, 16, v216
	v_and_b32_e32 v169, 0xffff0000, v216
	v_lshlrev_b32_e32 v170, 16, v217
	v_and_b32_e32 v171, 0xffff0000, v217
	v_lshlrev_b32_e32 v172, 16, v248
	v_and_b32_e32 v173, 0xffff0000, v248
	v_lshlrev_b32_e32 v174, 16, v249
	v_and_b32_e32 v175, 0xffff0000, v249
	v_pk_fma_f32 v[26:27], v[26:27], v[170:171], v[174:175]
	v_pk_fma_f32 v[24:25], v[24:25], v[168:169], v[172:173]
	s_nop 0
	v_cvt_pk_bf16_f32 v24, v24, v25
	v_cvt_pk_bf16_f32 v25, v26, v27
	global_store_dwordx2 v166, v[24:25], s[52:53] offset:32
	v_lshlrev_b32_e32 v168, 16, v218
	v_and_b32_e32 v169, 0xffff0000, v218
	v_lshlrev_b32_e32 v170, 16, v219
	v_and_b32_e32 v171, 0xffff0000, v219
	v_lshlrev_b32_e32 v172, 16, v250
	v_and_b32_e32 v173, 0xffff0000, v250
	v_lshlrev_b32_e32 v174, 16, v251
	v_and_b32_e32 v175, 0xffff0000, v251
	v_pk_fma_f32 v[22:23], v[22:23], v[170:171], v[174:175]
	v_pk_fma_f32 v[20:21], v[20:21], v[168:169], v[172:173]
	s_nop 0
	v_cvt_pk_bf16_f32 v20, v20, v21
	v_cvt_pk_bf16_f32 v21, v22, v23
	global_store_dwordx2 v166, v[20:21], s[52:53] offset:256
	v_lshlrev_b32_e32 v168, 16, v220
	v_and_b32_e32 v169, 0xffff0000, v220
	v_lshlrev_b32_e32 v170, 16, v221
	v_and_b32_e32 v171, 0xffff0000, v221
	v_lshlrev_b32_e32 v172, 16, v252
	v_and_b32_e32 v173, 0xffff0000, v252
	v_lshlrev_b32_e32 v174, 16, v253
	v_and_b32_e32 v175, 0xffff0000, v253
	v_pk_fma_f32 v[18:19], v[18:19], v[170:171], v[174:175]
	v_pk_fma_f32 v[16:17], v[16:17], v[168:169], v[172:173]
	s_nop 0
	v_cvt_pk_bf16_f32 v16, v16, v17
	v_cvt_pk_bf16_f32 v17, v18, v19
	global_store_dwordx2 v166, v[16:17], s[52:53] offset:288
	v_lshlrev_b32_e32 v168, 16, v222
	v_and_b32_e32 v169, 0xffff0000, v222
	v_lshlrev_b32_e32 v170, 16, v223
	v_and_b32_e32 v171, 0xffff0000, v223
	v_lshlrev_b32_e32 v172, 16, v182
	v_and_b32_e32 v173, 0xffff0000, v182
	v_lshlrev_b32_e32 v174, 16, v183
	v_and_b32_e32 v175, 0xffff0000, v183
	v_pk_fma_f32 v[14:15], v[14:15], v[170:171], v[174:175]
	v_pk_fma_f32 v[12:13], v[12:13], v[168:169], v[172:173]
	s_nop 0
	v_cvt_pk_bf16_f32 v12, v12, v13
	v_cvt_pk_bf16_f32 v13, v14, v15
	global_store_dwordx2 v167, v[12:13], s[52:53]
	v_lshlrev_b32_e32 v168, 16, v224
	v_and_b32_e32 v169, 0xffff0000, v224
	v_lshlrev_b32_e32 v170, 16, v225
	v_and_b32_e32 v171, 0xffff0000, v225
	v_lshlrev_b32_e32 v172, 16, v184
	v_and_b32_e32 v173, 0xffff0000, v184
	v_lshlrev_b32_e32 v174, 16, v185
	v_and_b32_e32 v175, 0xffff0000, v185
	v_pk_fma_f32 v[10:11], v[10:11], v[170:171], v[174:175]
	v_pk_fma_f32 v[8:9], v[8:9], v[168:169], v[172:173]
	s_nop 0
	v_cvt_pk_bf16_f32 v8, v8, v9
	v_cvt_pk_bf16_f32 v9, v10, v11
	global_store_dwordx2 v167, v[8:9], s[52:53] offset:32
	v_lshlrev_b32_e32 v168, 16, v226
	v_and_b32_e32 v169, 0xffff0000, v226
	v_lshlrev_b32_e32 v170, 16, v227
	v_and_b32_e32 v171, 0xffff0000, v227
	v_lshlrev_b32_e32 v172, 16, v186
	v_and_b32_e32 v173, 0xffff0000, v186
	v_lshlrev_b32_e32 v174, 16, v187
	v_and_b32_e32 v175, 0xffff0000, v187
	v_pk_fma_f32 v[6:7], v[6:7], v[170:171], v[174:175]
	v_pk_fma_f32 v[4:5], v[4:5], v[168:169], v[172:173]
	s_nop 0
	v_cvt_pk_bf16_f32 v4, v4, v5
	v_cvt_pk_bf16_f32 v5, v6, v7
	global_store_dwordx2 v167, v[4:5], s[52:53] offset:256
	v_lshlrev_b32_e32 v168, 16, v228
	v_and_b32_e32 v169, 0xffff0000, v228
	v_lshlrev_b32_e32 v170, 16, v229
	v_and_b32_e32 v171, 0xffff0000, v229
	v_lshlrev_b32_e32 v172, 16, v190
	v_and_b32_e32 v173, 0xffff0000, v190
	v_lshlrev_b32_e32 v174, 16, v191
	v_and_b32_e32 v175, 0xffff0000, v191
	v_pk_fma_f32 v[2:3], v[2:3], v[170:171], v[174:175]
	v_pk_fma_f32 v[0:1], v[0:1], v[168:169], v[172:173]
	s_nop 0
	v_cvt_pk_bf16_f32 v0, v0, v1
	v_cvt_pk_bf16_f32 v1, v2, v3
	global_store_dwordx2 v167, v[0:1], s[52:53] offset:288
	s_cbranch_vccnz .LBB0_864
	s_andn2_b64 vcc, exec, s[46:47]
	s_cbranch_vccnz .LBB0_863
	s_barrier
	s_branch .LBB0_863
